# prompt-attention loop: removed compiler vmcnt(3..0) ladder that drained the LDS-DMA ring every tile (Q loads already retired by pre-loop vmcnt(10))
# speedup vs baseline: 1.0310x; 1.0310x over previous
; #define LAS __attribute__((address_space(3)))
; DI void glds16(const void* gbase, unsigned voff, unsigned lds_dst) { unsigned keep;
;     asm volatile("s_mov_b32 %0, m0\n\ts_mov_b32 m0, %3\n\ts_nop 0\n\tglobal_load_lds_dwordx4 %1, %2\n\ts_mov_b32 m0, %0" : "=&s"(keep) : "v"(voff), "s"(gbase), "s"(lds_dst) : "memory"); }
; DI void dma_tile(LAS char* slot, const bf16_t* Kg, const bf16_t* Vg, const unsigned (&poff)[5], int wid) {
; #pragma unroll
;     for (int j = 0; j < 5; ++j) { const int g0 = wid * 5 + j, gi = g0 > 36 ? 36 : g0;
;         { const bool isk = gi < 17; glds16(isk ? (const void*)Kg : (const void*)Vg, poff[j], (unsigned)(size_t)(isk ? slot + gi * 1024 : slot + SLOT_V + (gi - 17) * 1024)); } }
; DI void attn_unit(const Params& p, LAS unsigned char* ldsu, int kind, int b, int h, int u, float lam) {
;     ...
;         auto stage = [&](int t) { if (t >= ntl) t = ntl - 1; const int row0 = t == 0 ? ROW_M : b * SEQ + (t - 1) * 64;
;             dma_tile(lds + (t & 3) * SLOT_B, KB + (size_t)row0 * 512 + hc, VB + (size_t)row0 * 512 + hc, poff, wid); };
;         stage(0); stage(1); stage(2);
;         asm volatile("s_waitcnt vmcnt(10)" ::: "memory");
;         __syncthreads();
;         for (int t = 0; t < ntl; ++t) {
;             stage(t + 3);
;             const LAS char* sp = lds + (t & 3) * SLOT_B;
;             if (t <= my_last) { bf16x8 pf[4]; attn_qk(sp + kboff, qf, pf, l); attn_pv(sp + vboff, pf, O); }
.LBB0_745:
	s_add_i32 s22, s21, 3
	s_min_i32 s24, s22, s6
	s_lshl_b32 s22, s24, 6
	s_add_i32 s22, s17, s22
	s_and_b32 s24, s24, 3
	s_ashr_i32 s23, s22, 31
	s_mul_i32 s24, s24, 0x9400
	s_add_i32 s24, s24, 0
	s_lshl_b64 s[22:23], s[22:23], 10
	s_add_u32 s25, s16, s22
	s_addc_u32 s26, s18, s23
	s_add_u32 s27, s19, s22
	s_addc_u32 s34, s20, s23
	s_and_b64 s[22:23], s[0:1], exec
	s_cselect_b32 s23, s26, s34
	s_cselect_b32 s22, s25, s27
	s_add_i32 s35, s24, s7
	s_mov_b32 s36, m0
	s_mov_b32 m0, s35
	s_nop 0
	global_load_lds_dwordx4 v132, s[22:23]
	s_mov_b32 m0, s36
	s_add_i32 s35, s24, s10
	s_addk_i32 s35, 0x400
	s_mov_b32 s36, m0
	s_mov_b32 m0, s35
	s_nop 0
	global_load_lds_dwordx4 v131, s[22:23]
	s_mov_b32 m0, s36
	s_and_b64 s[22:23], exec, s[8:9]
	s_cselect_b32 s23, s26, s34
	s_cselect_b32 s22, s25, s27
	s_add_i32 s25, s24, s11
	s_addk_i32 s25, 0x800
	s_mov_b32 s26, m0
	s_mov_b32 m0, s25
	s_nop 0
	global_load_lds_dwordx4 v130, s[22:23]
	s_mov_b32 m0, s26
	s_add_i32 s25, s24, s12
	s_addk_i32 s25, 0xc00
	s_mov_b32 s26, m0
	s_mov_b32 m0, s25
	s_nop 0
	global_load_lds_dwordx4 v129, s[22:23]
	s_mov_b32 m0, s26
	s_add_i32 s24, s24, s13
	s_addk_i32 s24, 0x1000
	s_mov_b32 s25, m0
	s_mov_b32 m0, s24
	s_nop 0
	global_load_lds_dwordx4 v133, s[22:23]
	s_mov_b32 m0, s25
	s_cmp_gt_i32 s21, s29
	s_cbranch_scc1 .LBB0_744
; #define LAS __attribute__((address_space(3)))
; DI void attn_qk(const LAS char* kb, const bf16x8 (&qf)[4], bf16x8 (&pf)[4], float& l) {
;     f32x16 zero;
; #pragma unroll
;     for (int i = 0; i < 16; ++i) zero[i] = 0.f;
;     bf16x8 k0[4], k1[4];
; #pragma unroll
;     for (int s = 0; s < 4; ++s) k0[s] = *(const LAS bf16x8*)(kb + 32 * s);
; #pragma unroll
;     for (int s = 0; s < 4; ++s) k1[s] = *(const LAS bf16x8*)(kb + 32 * KRS + 32 * s);
;     f32x16 st0 = MFMA32(k0[0], qf[0], zero), st1 = MFMA32(k1[0], qf[0], zero);
; #pragma unroll
;     for (int s = 1; s < 4; ++s) { st0 = MFMA32(k0[s], qf[s], st0); st1 = MFMA32(k1[s], qf[s], st1); }
;     SGB(0x100, 8); SGB(0x008, 8);
;     float sum = 0.f;
; #pragma unroll
;     for (int i = 0; i < 16; ++i) { const float e = __builtin_amdgcn_exp2f(st0[i]); st0[i] = e; sum += e; }
;     pf[0] = pack8(st0, 0); pf[1] = pack8(st0, 1);
; #pragma unroll
;     for (int i = 0; i < 16; ++i) { const float e = __builtin_amdgcn_exp2f(st1[i]); st1[i] = e; sum += e; }
;     pf[2] = pack8(st1, 0); pf[3] = pack8(st1, 1);
;     l += sum;
; }
; DI void attn_pv(const LAS char* vb, const bf16x8 (&pf)[4], f32x16 (&O)[4]) {
;     s16x4 va[8], vc[8];
; #pragma unroll
;     for (int ks = 0; ks < 4; ++ks) { va[2 * ks] = vtr(vb + ks * 16 * VRS); va[2 * ks + 1] = vtr(vb + (ks * 16 + 8) * VRS); }
; #pragma unroll
;     for (int ks = 0; ks < 4; ++ks) { vc[2 * ks] = vtr(vb + ks * 16 * VRS + 64); vc[2 * ks + 1] = vtr(vb + (ks * 16 + 8) * VRS + 64); }
; #pragma unroll
;     for (int ks = 0; ks < 4; ++ks) O[0] = MFMA32(cat4(va[2 * ks], va[2 * ks + 1]), pf[ks], O[0]);
; #pragma unroll
;     for (int ks = 0; ks < 4; ++ks) { va[2 * ks] = vtr(vb + ks * 16 * VRS + 128); va[2 * ks + 1] = vtr(vb + (ks * 16 + 8) * VRS + 128); }
;     SGB(0x100, 16); SGB(0x008, 4); SGB(0x100, 8);
; #pragma unroll
;     for (int ks = 0; ks < 4; ++ks) O[1] = MFMA32(cat4(vc[2 * ks], vc[2 * ks + 1]), pf[ks], O[1]);
; #pragma unroll
;     for (int ks = 0; ks < 4; ++ks) { vc[2 * ks] = vtr(vb + ks * 16 * VRS + 192); vc[2 * ks + 1] = vtr(vb + (ks * 16 + 8) * VRS + 192); }
;     SGB(0x008, 4); SGB(0x100, 8);
; #pragma unroll
;     for (int ks = 0; ks < 4; ++ks) O[2] = MFMA32(cat4(va[2 * ks], va[2 * ks + 1]), pf[ks], O[2]);
;     SGB(0x008, 4);
; #pragma unroll
;     for (int ks = 0; ks < 4; ++ks) O[3] = MFMA32(cat4(vc[2 * ks], vc[2 * ks + 1]), pf[ks], O[3]);
;     SGB(0x008, 4);
	s_and_b32 s22, s21, 3
	s_mul_i32 s22, s22, 0x9400
	s_add_i32 s22, s22, 0
	v_add_u32_e32 v0, s22, v174
	ds_read_b128 v[2:5], v0
	ds_read_b128 v[6:9], v0 offset:32
	ds_read_b128 v[10:13], v0 offset:64
	ds_read_b128 v[136:139], v0 offset:96
	ds_read_b128 v[80:83], v0 offset:8704
	ds_read_b128 v[140:143], v0 offset:8736
	ds_read_b128 v[144:147], v0 offset:8768
	ds_read_b128 v[148:151], v0 offset:8800
	s_waitcnt lgkmcnt(7)
	v_mfma_f32_32x32x16_bf16 v[96:111], v[2:5], v[112:115], 0
	s_waitcnt lgkmcnt(6)
	v_mfma_f32_32x32x16_bf16 v[96:111], v[6:9], v[116:119], v[96:111]
	s_waitcnt lgkmcnt(3)
	v_mfma_f32_32x32x16_bf16 v[80:95], v[80:83], v[112:115], 0
	s_nop 0
	v_mfma_f32_32x32x16_bf16 v[96:111], v[10:13], v[120:123], v[96:111]
	s_nop 0
	v_mfma_f32_32x32x16_bf16 v[96:111], v[136:139], v[124:127], v[96:111]
	s_waitcnt lgkmcnt(2)
	v_mfma_f32_32x32x16_bf16 v[80:95], v[140:143], v[116:119], v[80:95]
	s_nop 9
	v_exp_f32_e32 v0, v96
	v_exp_f32_e32 v3, v97
	v_exp_f32_e32 v4, v98
	v_exp_f32_e32 v5, v99
	v_add_f32_e32 v2, 0, v0
	v_exp_f32_e32 v6, v100
	v_add_f32_e32 v2, v3, v2
	s_waitcnt lgkmcnt(1)
	v_mfma_f32_32x32x16_bf16 v[80:95], v[144:147], v[120:123], v[80:95]
	v_exp_f32_e32 v7, v101
	v_add_f32_e32 v2, v4, v2
	v_exp_f32_e32 v8, v102
	v_add_f32_e32 v2, v5, v2
	v_exp_f32_e32 v9, v103
	v_add_f32_e32 v2, v6, v2
	v_exp_f32_e32 v10, v104
	s_waitcnt lgkmcnt(0)
	v_mfma_f32_32x32x16_bf16 v[80:95], v[148:151], v[124:127], v[80:95]
	v_add_f32_e32 v2, v7, v2
	v_exp_f32_e32 v11, v105
	v_add_f32_e32 v2, v8, v2
	v_exp_f32_e32 v12, v106
	v_add_f32_e32 v2, v9, v2
	v_exp_f32_e32 v13, v107
	v_add_f32_e32 v2, v10, v2
	v_exp_f32_e32 v14, v108
	v_add_f32_e32 v2, v11, v2
	v_exp_f32_e32 v15, v109
	v_add_f32_e32 v2, v12, v2
	v_exp_f32_e32 v100, v110
	v_add_f32_e32 v2, v13, v2
	v_exp_f32_e32 v101, v111
	v_add_f32_e32 v2, v14, v2
	v_cvt_pk_bf16_f32 v96, v0, v3
	v_exp_f32_e32 v0, v80
	v_add_f32_e32 v2, v15, v2
	v_cvt_pk_bf16_f32 v98, v6, v7
	v_exp_f32_e32 v7, v81
	v_add_f32_e32 v2, v100, v2
	v_cvt_pk_bf16_f32 v99, v8, v9
	v_exp_f32_e32 v8, v82
	v_add_f32_e32 v102, v101, v2
	v_exp_f32_e32 v9, v83
	v_cvt_pk_bf16_f32 v2, v10, v11
	v_add_f32_e32 v6, v0, v102
	v_exp_f32_e32 v10, v84
	v_add_f32_e32 v6, v7, v6
	v_exp_f32_e32 v11, v85
	v_cvt_pk_bf16_f32 v3, v12, v13
	v_add_f32_e32 v6, v8, v6
	v_exp_f32_e32 v12, v86
	v_add_f32_e32 v6, v9, v6
	v_exp_f32_e32 v13, v87
	v_cvt_pk_bf16_f32 v97, v4, v5
	v_cvt_pk_bf16_f32 v4, v14, v15
	v_add_f32_e32 v6, v10, v6
	v_exp_f32_e32 v14, v88
	v_add_f32_e32 v6, v11, v6
	v_exp_f32_e32 v15, v89
	v_add_f32_e32 v6, v12, v6
	v_exp_f32_e32 v80, v90
	v_add_f32_e32 v6, v13, v6
	v_exp_f32_e32 v81, v91
	v_add_f32_e32 v6, v14, v6
	v_exp_f32_e32 v82, v92
	v_add_f32_e32 v6, v15, v6
	v_exp_f32_e32 v83, v93
	v_add_f32_e32 v6, v80, v6
	v_exp_f32_e32 v84, v94
	v_add_f32_e32 v6, v81, v6
	v_exp_f32_e32 v85, v95
	v_add_f32_e32 v6, v82, v6
	v_add_f32_e32 v6, v83, v6
	v_add_f32_e32 v6, v84, v6
	v_add_f32_e32 v86, v85, v6
	v_cvt_pk_bf16_f32 v6, v0, v7
	v_add_u32_e32 v0, s22, v134
	v_cvt_pk_bf16_f32 v5, v100, v101
	ds_read_b64_tr_b16 v[100:101], v0 offset:17408
	ds_read_b64_tr_b16 v[102:103], v0 offset:19968
	s_waitcnt lgkmcnt(0)
	v_mfma_f32_32x32x16_bf16 v[64:79], v[100:103], v[96:99], v[64:79]
	ds_read_b64_tr_b16 v[100:101], v0 offset:17536
	ds_read_b64_tr_b16 v[102:103], v0 offset:20096
	ds_read_b64_tr_b16 v[104:105], v0 offset:22528
	ds_read_b64_tr_b16 v[106:107], v0 offset:25088
	v_cvt_pk_bf16_f32 v7, v8, v9
	v_cvt_pk_bf16_f32 v8, v10, v11
	v_cvt_pk_bf16_f32 v9, v12, v13
	s_waitcnt lgkmcnt(0)
	v_mfma_f32_32x32x16_bf16 v[64:79], v[104:107], v[2:5], v[64:79]
	ds_read_b64_tr_b16 v[104:105], v0 offset:22656
	ds_read_b64_tr_b16 v[106:107], v0 offset:25216
	ds_read_b64_tr_b16 v[108:109], v0 offset:27648
	ds_read_b64_tr_b16 v[110:111], v0 offset:30208
	v_cvt_pk_bf16_f32 v10, v14, v15
	v_cvt_pk_bf16_f32 v11, v80, v81
	v_cvt_pk_bf16_f32 v12, v82, v83
	s_waitcnt lgkmcnt(0)
	v_mfma_f32_32x32x16_bf16 v[64:79], v[108:111], v[6:9], v[64:79]
	ds_read_b64_tr_b16 v[108:109], v0 offset:27776
	ds_read_b64_tr_b16 v[110:111], v0 offset:30336
	ds_read_b64_tr_b16 v[136:137], v0 offset:32768
	ds_read_b64_tr_b16 v[138:139], v0 offset:35328
	v_cvt_pk_bf16_f32 v13, v84, v85
	v_add_f32_e32 v175, v175, v86
	s_waitcnt lgkmcnt(0)
	v_mfma_f32_32x32x16_bf16 v[64:79], v[136:139], v[10:13], v[64:79]
	ds_read_b64_tr_b16 v[136:137], v0 offset:32896
	ds_read_b64_tr_b16 v[138:139], v0 offset:35456
	ds_read_b64_tr_b16 v[80:81], v0 offset:17472
	ds_read_b64_tr_b16 v[82:83], v0 offset:20032
	ds_read_b64_tr_b16 v[84:85], v0 offset:22592
	ds_read_b64_tr_b16 v[86:87], v0 offset:25152
	ds_read_b64_tr_b16 v[88:89], v0 offset:27712
	ds_read_b64_tr_b16 v[90:91], v0 offset:30272
	ds_read_b64_tr_b16 v[92:93], v0 offset:32832
	ds_read_b64_tr_b16 v[94:95], v0 offset:35392
	s_waitcnt lgkmcnt(6)
	v_mfma_f32_32x32x16_bf16 v[48:63], v[80:83], v[96:99], v[48:63]
	ds_read_b64_tr_b16 v[80:81], v0 offset:17600
	ds_read_b64_tr_b16 v[82:83], v0 offset:20160
	s_waitcnt lgkmcnt(6)
	v_mfma_f32_32x32x16_bf16 v[48:63], v[84:87], v[2:5], v[48:63]
	ds_read_b64_tr_b16 v[84:85], v0 offset:22720
	ds_read_b64_tr_b16 v[86:87], v0 offset:25280
	s_waitcnt lgkmcnt(6)
	v_mfma_f32_32x32x16_bf16 v[48:63], v[88:91], v[6:9], v[48:63]
	ds_read_b64_tr_b16 v[88:89], v0 offset:27840
	ds_read_b64_tr_b16 v[90:91], v0 offset:30400
	s_waitcnt lgkmcnt(6)
	v_mfma_f32_32x32x16_bf16 v[48:63], v[92:95], v[10:13], v[48:63]
	ds_read_b64_tr_b16 v[92:93], v0 offset:32960
	ds_read_b64_tr_b16 v[94:95], v0 offset:35520
	v_mfma_f32_32x32x16_bf16 v[32:47], v[100:103], v[96:99], v[32:47]
	s_waitcnt lgkmcnt(6)
	v_mfma_f32_32x32x16_bf16 v[16:31], v[80:83], v[96:99], v[16:31]
	v_mfma_f32_32x32x16_bf16 v[32:47], v[104:107], v[2:5], v[32:47]
	s_waitcnt lgkmcnt(4)
	v_mfma_f32_32x32x16_bf16 v[16:31], v[84:87], v[2:5], v[16:31]
	v_mfma_f32_32x32x16_bf16 v[32:47], v[108:111], v[6:9], v[32:47]
	s_waitcnt lgkmcnt(2)
	v_mfma_f32_32x32x16_bf16 v[16:31], v[88:91], v[6:9], v[16:31]
	v_mfma_f32_32x32x16_bf16 v[32:47], v[136:139], v[10:13], v[32:47]
	s_waitcnt lgkmcnt(0)
	v_mfma_f32_32x32x16_bf16 v[16:31], v[92:95], v[10:13], v[16:31]
	s_branch .LBB0_744
